# v21 (mini_ring consume rewrite) plus .p2align 6 at the five GEMM K-loop bodies to pin their placement
# speedup vs baseline: 1.0099x; 1.0099x over previous
; template <class Epi, class Sched, bool ALIGN_EPI = false, bool SP2 = false>
; __device__ __forceinline__ void gemm_phase(PG8_LAS unsigned char* lds, const Gemm g, const Sched& S, const Epi& E, int wave_u) {
;     ...
;         const bool has_next = S.next(ui + 1, nxt);
;         const char* nA = has_next ? (const char*)g.A + (size_t)nxt.pm * tstep : cA; const char* nB = has_next ? (const char*)g.Bt + (size_t)nxt.pn * tstep : cB;
;         for (int t = 0; t < nt; t += 2) {
;             const bool last = (t == nt - 2);
;             const char* a1 = cA + (size_t)(t + 1) * kstep;
;             const char* a2 = last ? nA : cA + (size_t)(t + 2) * kstep; const char* b2 = last ? nB : cB + (size_t)(t + 2) * kstep;
;             const char* a3 = a2 + kstep; const char* b3 = b2 + kstep;
;             if (last && has_next) { S.a_ready(nxt); epi_prefetch(E, nxt.pm, nxt.pn, evb + (unsigned)(((ui + 1) & 1) * EPV_BYTES), tid); }
.LBB0_142:
	s_ashr_i32 s27, s26, 31
	s_lshl_b64 s[0:1], s[26:27], 19
	s_add_u32 s28, s70, s0
	s_addc_u32 s29, s71, s1
	s_and_b64 s[0:1], s[10:11], exec
	s_cselect_b32 s53, s29, s89
	s_cselect_b32 s90, s28, s88
	s_ashr_i32 s25, s24, 31
	s_lshl_b64 s[0:1], s[24:25], 19
	v_readlane_b32 s30, v255, 43
	v_readlane_b32 s31, v255, 44
	s_add_u32 s30, s30, s0
	s_addc_u32 s31, s31, s1
	s_and_b64 s[0:1], s[10:11], exec
	s_cselect_b32 s25, s31, s65
	s_cselect_b32 s91, s30, s64
	s_lshl_b32 s0, s87, 12
	s_and_b32 s0, s0, 0x1000
	s_add_i32 s0, s0, s7
	s_lshl_b32 s46, s24, 8
	s_lshl_b64 s[44:45], s[26:27], 11
	s_ashr_i32 s47, s46, 31
	s_add_i32 s27, s0, 0x800
	s_add_u32 s88, s88, 0x40080
	s_addc_u32 s89, s89, 0
	s_add_u32 s64, s64, 0x100
	v_lshl_add_u64 v[130:131], s[46:47], 2, v[178:179]
	v_lshl_add_u64 v[132:133], v[180:181], 0, s[44:45]
	s_addc_u32 s65, s65, 0
	s_mov_b32 s84, -2
	s_branch .LBB0_144
	.p2align 6

; template <class Epi, class Sched, bool ALIGN_EPI = false, bool SP2 = false>
; __device__ __forceinline__ void gemm_phase(PG8_LAS unsigned char* lds, const Gemm g, const Sched& S, const Epi& E, int wave_u) {
;     ...
;         const bool has_next = S.next(ui + 1, nxt);
;         const char* nA = has_next ? (const char*)g.A + (size_t)nxt.pm * tstep : cA; const char* nB = has_next ? (const char*)g.Bt + (size_t)nxt.pn * tstep : cB;
;         for (int t = 0; t < nt; t += 2) {
;             const bool last = (t == nt - 2);
;             const char* a1 = cA + (size_t)(t + 1) * kstep;
;             const char* a2 = last ? nA : cA + (size_t)(t + 2) * kstep; const char* b2 = last ? nB : cB + (size_t)(t + 2) * kstep;
;             const char* a3 = a2 + kstep; const char* b3 = b2 + kstep;
;             if (last && has_next) { S.a_ready(nxt); epi_prefetch(E, nxt.pm, nxt.pn, evb + (unsigned)(((ui + 1) & 1) * EPV_BYTES), tid); }
.LBB0_263:
	s_ashr_i32 s31, s30, 31
	s_lshl_b64 s[0:1], s[30:31], 19
	s_add_u32 s34, s70, s0
	s_addc_u32 s35, s71, s1
	s_and_b64 s[0:1], s[10:11], exec
	s_cselect_b32 s13, s35, s89
	s_cselect_b32 s19, s34, s88
	s_ashr_i32 s17, s16, 31
	s_lshl_b64 s[0:1], s[16:17], 19
	v_readlane_b32 s14, v255, 43
	v_readlane_b32 s15, v255, 44
	s_add_u32 s14, s14, s0
	s_addc_u32 s15, s15, s1
	s_and_b64 s[0:1], s[10:11], exec
	s_cselect_b32 s17, s15, s65
	s_cselect_b32 s29, s14, s64
	s_lshl_b32 s0, s18, 12
	s_and_b32 s0, s0, 0x1000
	s_add_i32 s0, s0, s84
	s_lshl_b32 s44, s16, 8
	s_lshl_b64 s[40:41], s[30:31], 11
	s_ashr_i32 s45, s44, 31
	s_add_i32 s31, s0, 0x800
	s_add_u32 s88, s88, 0x40080
	s_addc_u32 s89, s89, 0
	v_lshl_add_u64 v[128:129], v[188:189], 0, s[40:41]
	s_add_u32 s40, s64, 0x100
	s_addc_u32 s41, s65, 0
	v_readlane_b32 s64, v255, 16
	v_lshl_add_u64 v[126:127], s[44:45], 2, v[186:187]
	s_mov_b32 s52, -2
	v_readlane_b32 s65, v255, 17
	s_branch .LBB0_265
	.p2align 6

; template <class Epi, class Sched, bool ALIGN_EPI = false, bool SP2 = false>
; __device__ __forceinline__ void gemm_phase(PG8_LAS unsigned char* lds, const Gemm g, const Sched& S, const Epi& E, int wave_u) {
;     ...
;         const bool has_next = S.next(ui + 1, nxt);
;         const char* nA = has_next ? (const char*)g.A + (size_t)nxt.pm * tstep : cA; const char* nB = has_next ? (const char*)g.Bt + (size_t)nxt.pn * tstep : cB;
;         for (int t = 0; t < nt; t += 2) {
;             const bool last = (t == nt - 2);
;             const char* a1 = cA + (size_t)(t + 1) * kstep;
;             const char* a2 = last ? nA : cA + (size_t)(t + 2) * kstep; const char* b2 = last ? nB : cB + (size_t)(t + 2) * kstep;
;             const char* a3 = a2 + kstep; const char* b3 = b2 + kstep;
;             if (last && has_next) { S.a_ready(nxt); epi_prefetch(E, nxt.pm, nxt.pn, evb + (unsigned)(((ui + 1) & 1) * EPV_BYTES), tid); }
.LBB0_979:
	s_ashr_i32 s21, s20, 31
	s_lshl_b64 s[0:1], s[20:21], 19
	v_readlane_b32 s22, v250, 11
	v_readlane_b32 s23, v250, 12
	s_add_u32 s22, s22, s0
	s_addc_u32 s23, s23, s1
	s_and_b64 s[0:1], s[12:13], exec
	s_cselect_b32 s52, s23, s65
	s_cselect_b32 s53, s22, s64
	s_ashr_i32 s19, s18, 31
	s_lshl_b64 s[0:1], s[18:19], 19
	s_add_u32 s24, s30, s0
	s_addc_u32 s25, s31, s1
	s_and_b64 s[0:1], s[12:13], exec
	s_cselect_b32 s19, s25, s61
	s_cselect_b32 s96, s24, s60
	s_lshl_b32 s0, s79, 12
	s_and_b32 s0, s0, 0x1000
	s_add_i32 s0, s0, s59
	s_lshl_b32 s46, s18, 8
	s_lshl_b64 s[44:45], s[20:21], 11
	s_ashr_i32 s47, s46, 31
	s_add_i32 s21, s0, 0x800
	s_add_u32 s64, s64, 0x40080
	s_addc_u32 s65, s65, 0
	s_add_u32 s60, s60, 0x100
	v_lshl_add_u64 v[50:51], s[46:47], 2, v[206:207]
	v_lshl_add_u64 v[52:53], v[208:209], 0, s[44:45]
	s_addc_u32 s61, s61, 0
	s_mov_b32 s84, -2
	s_branch .LBB0_981
	.p2align 6

; template <class Epi, class Sched, bool ALIGN_EPI = false, bool SP2 = false>
; __device__ __forceinline__ void gemm_phase(PG8_LAS unsigned char* lds, const Gemm g, const Sched& S, const Epi& E, int wave_u) {
;     ...
;         const bool has_next = S.next(ui + 1, nxt);
;         const char* nA = has_next ? (const char*)g.A + (size_t)nxt.pm * tstep : cA; const char* nB = has_next ? (const char*)g.Bt + (size_t)nxt.pn * tstep : cB;
;         for (int t = 0; t < nt; t += 2) {
;             const bool last = (t == nt - 2);
;             const char* a1 = cA + (size_t)(t + 1) * kstep;
;             const char* a2 = last ? nA : cA + (size_t)(t + 2) * kstep; const char* b2 = last ? nB : cB + (size_t)(t + 2) * kstep;
;             const char* a3 = a2 + kstep; const char* b3 = b2 + kstep;
;             if (last && has_next) { S.a_ready(nxt); epi_prefetch(E, nxt.pm, nxt.pn, evb + (unsigned)(((ui + 1) & 1) * EPV_BYTES), tid); }
.LBB0_1174:
	s_ashr_i32 s23, s22, 31
	s_lshl_b64 s[0:1], s[22:23], 19
	s_add_u32 s24, s72, s0
	s_addc_u32 s25, s73, s1
	s_and_b64 s[0:1], s[10:11], exec
	s_cselect_b32 s90, s25, s61
	s_cselect_b32 s91, s24, s60
	s_ashr_i32 s21, s20, 31
	s_lshl_b64 s[0:1], s[20:21], 19
	s_add_u32 s26, s12, s0
	s_addc_u32 s27, s13, s1
	s_and_b64 s[0:1], s[10:11], exec
	s_cselect_b32 s21, s27, s35
	s_cselect_b32 s96, s26, s34
	s_lshl_b32 s0, s89, 12
	s_and_b32 s0, s0, 0x1000
	s_add_i32 s0, s0, s40
	s_lshl_b32 s46, s20, 8
	s_lshl_b64 s[44:45], s[22:23], 11
	s_ashr_i32 s47, s46, 31
	s_add_i32 s23, s0, 0x800
	s_add_u32 s60, s60, 0x40080
	s_addc_u32 s61, s61, 0
	s_add_u32 s84, s34, 0x100
	v_lshl_add_u64 v[130:131], s[46:47], 2, v[170:171]
	v_lshl_add_u64 v[132:133], v[172:173], 0, s[44:45]
	s_addc_u32 s85, s35, 0
	s_mov_b32 s1, -2
	s_branch .LBB0_1176
	.p2align 6

; template <class Epi, class Sched, bool ALIGN_EPI = false, bool SP2 = false>
; __device__ __forceinline__ void gemm_phase(PG8_LAS unsigned char* lds, const Gemm g, const Sched& S, const Epi& E, int wave_u) {
;     ...
;         const bool has_next = S.next(ui + 1, nxt);
;         const char* nA = has_next ? (const char*)g.A + (size_t)nxt.pm * tstep : cA; const char* nB = has_next ? (const char*)g.Bt + (size_t)nxt.pn * tstep : cB;
;         for (int t = 0; t < nt; t += 2) {
;             const bool last = (t == nt - 2);
;             const char* a1 = cA + (size_t)(t + 1) * kstep;
;             const char* a2 = last ? nA : cA + (size_t)(t + 2) * kstep; const char* b2 = last ? nB : cB + (size_t)(t + 2) * kstep;
;             const char* a3 = a2 + kstep; const char* b3 = b2 + kstep;
;             if (last && has_next) { S.a_ready(nxt); epi_prefetch(E, nxt.pm, nxt.pn, evb + (unsigned)(((ui + 1) & 1) * EPV_BYTES), tid); }
.LBB0_1427:
	s_lshl_b32 s0, s96, 12
	s_and_b32 s0, s0, 0x1000
	s_add_i32 s0, s0, s85
	s_ashr_i32 s21, s20, 31
	s_lshl_b32 s44, s53, 8
	s_lshl_b64 s[28:29], s[20:21], 11
	s_ashr_i32 s45, s44, 31
	s_add_i32 s21, s0, 0x800
	v_lshl_add_u64 v[52:53], v[208:209], 0, s[28:29]
	s_add_u32 s28, s64, 0xb0080
	s_addc_u32 s29, s65, 0
	s_add_u32 s60, s60, 0x100
	v_lshl_add_u64 v[50:51], s[44:45], 2, v[206:207]
	s_addc_u32 s61, s61, 0
	s_mov_b32 s1, -2
	s_branch .LBB0_1429
	.p2align 6
